# attention bound flag: poll every ~1300 cycles (s_sleep 20) instead of ~300 to cut polling traffic
# speedup vs baseline: 1.0010x; 1.0010x over previous
.Lkm_spin:
	global_load_dword v45, v133, s[24:25] sc1
	s_waitcnt vmcnt(0)
	v_readfirstlane_b32 s5, v45
	s_cmp_lg_u32 s5, 0
	s_cbranch_scc1 .Lkm_ready
	s_sleep 20
	s_branch .Lkm_spin
